# MoBA inner loop: one workgroup barrier per two 64-key steps (4 LDS pair slots, DMA two pairs ahead)
# speedup vs baseline: 1.0375x; 1.0004x over previous
; #define LAS __attribute__((address_space(3)))
; template <int l> __device__ __forceinline__ void layer_body(const Args& args, LAS unsigned char* lds, const XcdBarrier& bar) {
;     ...
;             for (int rep = 0; rep < NREP(4); ++rep) for (int w = bx; w < 256; w += G) { const int b = w & 7, kvh = (w >> 3) & 3, uu = w >> 5;
;                 for (int jj = 0; jj < 4; ++jj) { const int jg = (jj == 0) ? uu : (jj == 1) ? 15 - uu : (jj == 2) ? 16 + uu : 31 - uu;
;                     const int j = jg * 4 + (wave >> 1), jmax = jg * 4 + 3, hd = kvh * 2 + (wave & 1), own = j >> 3, q0g = b * SEQ + j * 32;
;                     const LAS float* tb = tb0_ + hd * TABW; const float b128 = tb[TPAD + 128];
;                     const bf16* kgu = KPAN + (size_t)(b * 4 + kvh) * 128 * 4096; const bf16* vgu = VPAN + (size_t)(b * 4 + kvh) * 128 * 4096; const unsigned so = (unsigned)tid * 8u;
;     ...
;                     DMA_PAIR(0, 0);
;                     bf16x8 qf[8];
; #pragma unroll
;                     for (int s = 0; s < 8; ++s) qf[s] = *(const bf16x8*)(Z + (size_t)(q0g + r) * OD_IN + hd * 128 + 16 * s + 8 * hh);
;                     unsigned selmask = 0u;
;                     if (own > 0) {
;                         f32x16 gt;
; #pragma unroll
;                         for (int i = 0; i < 16; ++i) gt[i] = 0.f;
;                         const long long* ks = (const long long*)KSUM + ((size_t)(b * 4 + kvh) * 16 + (r & 15)) * 128 + 8 * hh;
; #pragma unroll
;                         for (int s = 0; s < 8; ++s) { f32x4 a0, a1;
; #pragma unroll
;                             for (int e = 0; e < 4; ++e) { a0[e] = (float)ks[16 * s + e] * (1.0f / 4294967296.0f); a1[e] = (float)ks[16 * s + 4 + e] * (1.0f / 4294967296.0f); }
;                             v4u hi; hi.x = cvtpk(a0[0], a0[1]); hi.y = cvtpk(a0[2], a0[3]); hi.z = cvtpk(a1[0], a1[1]); hi.w = cvtpk(a1[2], a1[3]);
;                             v4u lo; lo.x = cvtpk(a0[0] - bflo(hi.x), a0[1] - bfhi(hi.x)); lo.y = cvtpk(a0[2] - bflo(hi.y), a0[3] - bfhi(hi.y)); lo.z = cvtpk(a1[0] - bflo(hi.z), a1[1] - bfhi(hi.z)); lo.w = cvtpk(a1[2] - bflo(hi.w), a1[3] - bfhi(hi.w));
;                             gt = MFMA32(__builtin_bit_cast(bf16x8, hi), qf[s], gt); gt = MFMA32(__builtin_bit_cast(bf16x8, lo), qf[s], gt); }
;                         float glo[8], ghi[8];
; #pragma unroll
.LBB0_1385:
	s_lshl_b32 s61, s63, 2
	s_add_i32 s61, s61, s14
	s_mov_b32 m0, s33
	s_lshl_b32 s64, s61, 5
	global_load_lds_dwordx4 v[158:159], off
	s_mov_b32 m0, s34
	v_add_u32_e32 v172, s64, v184
	global_load_lds_dwordx4 v[160:161], off
	s_mov_b32 m0, s47
	v_ashrrev_i32_e32 v173, 31, v172
	global_load_lds_dwordx4 v[162:163], off
	s_mov_b32 m0, s52
	v_lshlrev_b64 v[2:3], 12, v[172:173]
	global_load_lds_dwordx4 v[164:165], off
	s_mov_b64 s[100:101], 0x4000
	s_add_i32 m0, s33, 0x4000
	v_lshl_add_u64 v[218:219], v[158:159], 0, s[100:101]
	global_load_lds_dwordx4 v[218:219], off
	s_add_i32 m0, s34, 0x4000
	v_lshl_add_u64 v[218:219], v[160:161], 0, s[100:101]
	global_load_lds_dwordx4 v[218:219], off
	s_add_i32 m0, s47, 0x4000
	v_lshl_add_u64 v[218:219], v[162:163], 0, s[100:101]
	global_load_lds_dwordx4 v[218:219], off
	s_add_i32 m0, s52, 0x4000
	v_lshl_add_u64 v[218:219], v[164:165], 0, s[100:101]
	global_load_lds_dwordx4 v[218:219], off
	v_lshl_add_u64 v[2:3], v[166:167], 0, v[2:3]
	global_load_dwordx4 v[112:115], v[2:3], off
	global_load_dwordx4 v[116:119], v[2:3], off offset:32
	global_load_dwordx4 v[120:123], v[2:3], off offset:64
	global_load_dwordx4 v[124:127], v[2:3], off offset:96
	global_load_dwordx4 v[128:131], v[2:3], off offset:128
	global_load_dwordx4 v[132:135], v[2:3], off offset:160
	global_load_dwordx4 v[136:139], v[2:3], off offset:192
	global_load_dwordx4 v[140:143], v[2:3], off offset:224
	ds_read_b32 v188, v185 offset:640
	s_ashr_i32 s62, s61, 3
	s_cmp_lt_i32 s62, 1
	s_cbranch_scc1 .LBB0_1392
	global_load_dwordx4 v[6:9], v[170:171], off
	global_load_dwordx4 v[10:13], v[170:171], off offset:32
	global_load_dwordx4 v[14:17], v[170:171], off offset:16
	global_load_dwordx4 v[2:5], v[170:171], off offset:48
	global_load_dwordx4 v[18:21], v[170:171], off offset:176
	global_load_dwordx4 v[26:29], v[170:171], off offset:160
	global_load_dwordx4 v[22:25], v[170:171], off offset:144
	global_load_dwordx4 v[30:33], v[170:171], off offset:128
	s_cmp_eq_u32 s62, 1
	s_waitcnt vmcnt(0)
	v_xor_b32_e32 v34, v6, v7
	v_xor_b32_e32 v36, v10, v11
	v_xor_b32_e32 v38, v8, v9
	v_xor_b32_e32 v44, v2, v3
	v_ffbh_i32_e32 v1, v7
	v_ffbh_i32_e32 v35, v11
	v_ffbh_i32_e32 v37, v9
	v_ffbh_i32_e32 v43, v3
	v_ashrrev_i32_e32 v34, 31, v34
	v_ashrrev_i32_e32 v36, 31, v36
	v_ashrrev_i32_e32 v38, 31, v38
	v_ashrrev_i32_e32 v44, 31, v44
	v_add_u32_e32 v1, -1, v1
	v_add_u32_e32 v35, -1, v35
	v_add_u32_e32 v37, -1, v37
	v_add_u32_e32 v43, -1, v43
	v_add_u32_e32 v34, 32, v34
	v_add_u32_e32 v36, 32, v36
	v_add_u32_e32 v38, 32, v38
	v_add_u32_e32 v44, 32, v44
	v_min_u32_e32 v1, v1, v34
	v_min_u32_e32 v34, v35, v36
	v_min_u32_e32 v35, v37, v38
	v_min_u32_e32 v38, v43, v44
	v_xor_b32_e32 v40, v12, v13
	v_xor_b32_e32 v42, v14, v15
	v_lshlrev_b64 v[2:3], v38, v[2:3]
	v_ffbh_i32_e32 v39, v13
	v_ffbh_i32_e32 v41, v15
	v_ashrrev_i32_e32 v40, 31, v40
	v_ashrrev_i32_e32 v42, 31, v42
	v_lshlrev_b64 v[6:7], v1, v[6:7]
	v_min_u32_e32 v2, 1, v2
	v_xor_b32_e32 v46, v16, v17
	v_add_u32_e32 v39, -1, v39
	v_add_u32_e32 v41, -1, v41
	v_add_u32_e32 v40, 32, v40
	v_add_u32_e32 v42, 32, v42
	v_min_u32_e32 v6, 1, v6
	v_or_b32_e32 v2, v3, v2
	v_ffbh_i32_e32 v45, v17
	v_ashrrev_i32_e32 v46, 31, v46
	v_min_u32_e32 v36, v39, v40
	v_min_u32_e32 v37, v41, v42
	v_or_b32_e32 v6, v7, v6
	v_cvt_f32_i32_e32 v2, v2
	v_add_u32_e32 v45, -1, v45
	v_add_u32_e32 v46, 32, v46
	v_lshlrev_b64 v[10:11], v34, v[10:11]
	v_lshlrev_b64 v[8:9], v35, v[8:9]
	v_lshlrev_b64 v[12:13], v36, v[12:13]
	v_lshlrev_b64 v[14:15], v37, v[14:15]
	v_cvt_f32_i32_e32 v3, v6
	v_min_u32_e32 v39, v45, v46
	v_min_u32_e32 v10, 1, v10
	v_min_u32_e32 v8, 1, v8
	v_min_u32_e32 v12, 1, v12
	v_min_u32_e32 v14, 1, v14
	v_sub_u32_e32 v38, 32, v38
	v_lshlrev_b64 v[16:17], v39, v[16:17]
	v_or_b32_e32 v7, v11, v10
	v_or_b32_e32 v8, v9, v8
	v_or_b32_e32 v9, v13, v12
	v_or_b32_e32 v10, v15, v14
	v_sub_u32_e32 v1, 32, v1
	v_cvt_f32_i32_e32 v6, v7
	v_cvt_f32_i32_e32 v7, v8
	v_cvt_f32_i32_e32 v8, v9
	v_cvt_f32_i32_e32 v9, v10
	v_ldexp_f32 v10, v2, v38
	v_min_u32_e32 v2, 1, v16
	v_ldexp_f32 v1, v3, v1
	v_or_b32_e32 v2, v17, v2
	v_xor_b32_e32 v3, v4, v5
	v_cvt_f32_i32_e32 v16, v2
	v_ffbh_i32_e32 v2, v5
	v_ashrrev_i32_e32 v3, 31, v3
	v_sub_u32_e32 v34, 32, v34
	v_add_u32_e32 v2, -1, v2
	v_add_u32_e32 v3, 32, v3
	v_ldexp_f32 v6, v6, v34
	v_min_u32_e32 v34, v2, v3
	v_lshlrev_b64 v[2:3], v34, v[4:5]
	v_min_u32_e32 v2, 1, v2
	v_or_b32_e32 v2, v3, v2
	v_cvt_f32_i32_e32 v2, v2
	v_sub_u32_e32 v35, 32, v35
	v_ldexp_f32 v7, v7, v35
	v_sub_u32_e32 v5, 32, v34
	v_sub_u32_e32 v37, 32, v37
	v_mul_f32_e32 v11, 0x2f800000, v1
	v_mul_f32_e32 v13, 0x2f800000, v7
	v_ldexp_f32 v41, v2, v5
	v_ldexp_f32 v9, v9, v37
	v_mul_f32_e32 v37, 0x2f800000, v10
	v_sub_u32_e32 v17, 32, v39
	v_mul_f32_e32 v2, 0x2f800000, v41
	v_cvt_pk_bf16_f32 v34, v11, v13
	v_sub_u32_e32 v36, 32, v36
	v_ldexp_f32 v3, v16, v17
	v_cvt_pk_bf16_f32 v37, v37, v2
	v_lshlrev_b32_e32 v2, 16, v34
	v_ldexp_f32 v8, v8, v36
	v_mul_f32_e32 v15, 0x2f800000, v9
	v_mul_f32_e32 v4, 0x2f800000, v3
	v_fma_f32 v1, v1, s53, -v2
	v_and_b32_e32 v2, 0xffff0000, v34
	v_mul_f32_e32 v12, 0x2f800000, v6
	v_mul_f32_e32 v14, 0x2f800000, v8
	v_cvt_pk_bf16_f32 v35, v15, v4
	v_fma_f32 v2, v7, s53, -v2
	v_cvt_pk_bf16_f32 v36, v12, v14
	v_cvt_pk_bf16_f32 v38, v1, v2
	v_lshlrev_b32_e32 v1, 16, v35
	v_and_b32_e32 v2, 0xffff0000, v35
	v_fma_f32 v1, v9, s53, -v1
	v_fma_f32 v2, v3, s53, -v2
	v_cvt_pk_bf16_f32 v39, v1, v2
	v_lshlrev_b32_e32 v1, 16, v36
	v_and_b32_e32 v2, 0xffff0000, v36
	v_fma_f32 v1, v6, s53, -v1
	v_fma_f32 v2, v8, s53, -v2
	v_cvt_pk_bf16_f32 v40, v1, v2
	v_lshlrev_b32_e32 v1, 16, v37
	v_fma_f32 v1, v10, s53, -v1
; __device__ __forceinline__ unsigned cvtpk(float lo, float hi) { f32x2v_ v = {lo, hi}; bf16x2v_ b = __builtin_convertvector(v, bf16x2v_); return __builtin_bit_cast(unsigned, b); }
; __device__ __forceinline__ float bflo(unsigned w) { return __uint_as_float(w << 16); }
; __device__ __forceinline__ float bfhi(unsigned w) { return __uint_as_float(w & 0xffff0000u); }
; #define MFMA32(a, b, c) __builtin_amdgcn_mfma_f32_32x32x16_bf16((a), (b), (c), 0, 0, 0)
; template <int l> __device__ __forceinline__ void layer_body(const Args& args, LAS unsigned char* lds, const XcdBarrier& bar) {
;     ...
;                         const long long* ks = (const long long*)KSUM + ((size_t)(b * 4 + kvh) * 16 + (r & 15)) * 128 + 8 * hh;
; #pragma unroll
;                         for (int s = 0; s < 8; ++s) { f32x4 a0, a1;
; #pragma unroll
;                             for (int e = 0; e < 4; ++e) { a0[e] = (float)ks[16 * s + e] * (1.0f / 4294967296.0f); a1[e] = (float)ks[16 * s + 4 + e] * (1.0f / 4294967296.0f); }
;                             v4u hi; hi.x = cvtpk(a0[0], a0[1]); hi.y = cvtpk(a0[2], a0[3]); hi.z = cvtpk(a1[0], a1[1]); hi.w = cvtpk(a1[2], a1[3]);
;                             v4u lo; lo.x = cvtpk(a0[0] - bflo(hi.x), a0[1] - bfhi(hi.x)); lo.y = cvtpk(a0[2] - bflo(hi.y), a0[3] - bfhi(hi.y)); lo.z = cvtpk(a1[0] - bflo(hi.z), a1[1] - bfhi(hi.z)); lo.w = cvtpk(a1[2] - bflo(hi.w), a1[3] - bfhi(hi.w));
;                             gt = MFMA32(__builtin_bit_cast(bf16x8, hi), qf[s], gt); gt = MFMA32(__builtin_bit_cast(bf16x8, lo), qf[s], gt); }
	v_mfma_f32_32x32x16_bf16 v[2:17], v[34:37], v[112:115], 0
	v_and_b32_e32 v34, 0xffff0000, v37
	v_fma_f32 v34, v41, s53, -v34
	v_cvt_pk_bf16_f32 v41, v1, v34
	v_xor_b32_e32 v34, v30, v31
	v_ffbh_i32_e32 v1, v31
	v_ashrrev_i32_e32 v34, 31, v34
	v_add_u32_e32 v1, -1, v1
	v_add_u32_e32 v34, 32, v34
	v_min_u32_e32 v1, v1, v34
	v_lshlrev_b64 v[30:31], v1, v[30:31]
	v_min_u32_e32 v30, 1, v30
	v_xor_b32_e32 v34, v26, v27
	v_or_b32_e32 v30, v31, v30
	v_ffbh_i32_e32 v31, v27
	v_ashrrev_i32_e32 v34, 31, v34
	v_add_u32_e32 v31, -1, v31
	v_add_u32_e32 v34, 32, v34
	v_min_u32_e32 v31, v31, v34
	v_lshlrev_b64 v[26:27], v31, v[26:27]
	v_min_u32_e32 v26, 1, v26
	v_or_b32_e32 v26, v27, v26
	v_cvt_f32_i32_e32 v26, v26
	v_cvt_f32_i32_e32 v30, v30
	v_sub_u32_e32 v27, 32, v31
	v_sub_u32_e32 v1, 32, v1
	v_ldexp_f32 v43, v26, v27
	v_xor_b32_e32 v27, v32, v33
	v_ffbh_i32_e32 v26, v33
	v_ashrrev_i32_e32 v27, 31, v27
	v_add_u32_e32 v26, -1, v26
	v_add_u32_e32 v27, 32, v27
	v_ldexp_f32 v1, v30, v1
	v_min_u32_e32 v30, v26, v27
	v_lshlrev_b64 v[26:27], v30, v[32:33]
	v_min_u32_e32 v26, 1, v26
	v_or_b32_e32 v26, v27, v26
	v_xor_b32_e32 v27, v28, v29
	v_cvt_f32_i32_e32 v31, v26
	v_ffbh_i32_e32 v26, v29
	v_ashrrev_i32_e32 v27, 31, v27
	v_add_u32_e32 v26, -1, v26
	v_add_u32_e32 v27, 32, v27
	v_min_u32_e32 v32, v26, v27
	v_lshlrev_b64 v[26:27], v32, v[28:29]
	v_min_u32_e32 v26, 1, v26
	v_or_b32_e32 v26, v27, v26
	v_cvt_f32_i32_e32 v26, v26
	v_sub_u32_e32 v27, 32, v32
	v_sub_u32_e32 v30, 32, v30
	v_ldexp_f32 v45, v31, v30
	v_ldexp_f32 v47, v26, v27
	v_xor_b32_e32 v27, v22, v23
	v_ffbh_i32_e32 v26, v23
	v_ashrrev_i32_e32 v27, 31, v27
	global_load_dwordx4 v[30:33], v[170:171], off offset:272
	global_load_dwordx4 v[34:37], v[170:171], off offset:256
	v_add_u32_e32 v26, -1, v26
	v_add_u32_e32 v27, 32, v27
	v_min_u32_e32 v26, v26, v27
	v_lshlrev_b64 v[22:23], v26, v[22:23]
	v_min_u32_e32 v22, 1, v22
	v_or_b32_e32 v22, v23, v22
	v_sub_u32_e32 v23, 32, v26
	v_ffbh_i32_e32 v26, v19
	v_mfma_f32_32x32x16_bf16 v[2:17], v[38:41], v[112:115], v[2:17]
	v_add_u32_e32 v49, -1, v26
	global_load_dwordx4 v[26:29], v[170:171], off offset:304
	global_load_dwordx4 v[38:41], v[170:171], off offset:288
	v_xor_b32_e32 v50, v18, v19
	v_ashrrev_i32_e32 v50, 31, v50
	v_add_u32_e32 v50, 32, v50
	v_min_u32_e32 v49, v49, v50
	v_lshlrev_b64 v[18:19], v49, v[18:19]
	v_min_u32_e32 v18, 1, v18
	v_or_b32_e32 v18, v19, v18
	v_cvt_f32_i32_e32 v18, v18
	v_sub_u32_e32 v19, 32, v49
	v_cvt_f32_i32_e32 v22, v22
	v_mul_f32_e32 v42, 0x2f800000, v1
	v_ldexp_f32 v49, v18, v19
	v_xor_b32_e32 v19, v24, v25
	v_ffbh_i32_e32 v18, v25
	v_ashrrev_i32_e32 v19, 31, v19
	v_add_u32_e32 v18, -1, v18
	v_add_u32_e32 v19, 32, v19
	v_min_u32_e32 v51, v18, v19
	v_lshlrev_b64 v[18:19], v51, v[24:25]
	v_min_u32_e32 v18, 1, v18
	v_or_b32_e32 v18, v19, v18
	v_xor_b32_e32 v19, v20, v21
	v_cvt_f32_i32_e32 v24, v18
	v_ffbh_i32_e32 v18, v21
	v_ashrrev_i32_e32 v19, 31, v19
	v_add_u32_e32 v18, -1, v18
	v_add_u32_e32 v19, 32, v19
	v_sub_u32_e32 v25, 32, v51
	v_min_u32_e32 v51, v18, v19
	v_lshlrev_b64 v[18:19], v51, v[20:21]
	v_min_u32_e32 v18, 1, v18
	v_or_b32_e32 v18, v19, v18
	v_cvt_f32_i32_e32 v18, v18
	v_mul_f32_e32 v46, 0x2f800000, v45
	v_ldexp_f32 v23, v22, v23
	v_ldexp_f32 v24, v24, v25
	v_sub_u32_e32 v20, 32, v51
	v_mul_f32_e32 v22, 0x2f800000, v23
	v_mul_f32_e32 v19, 0x2f800000, v24
	v_ldexp_f32 v25, v18, v20
	v_cvt_pk_bf16_f32 v18, v42, v46
	v_cvt_pk_bf16_f32 v19, v22, v19
	v_lshlrev_b32_e32 v22, 16, v18
	v_fma_f32 v1, v1, s53, -v22
	v_and_b32_e32 v22, 0xffff0000, v18
	v_mul_f32_e32 v44, 0x2f800000, v43
	v_mul_f32_e32 v48, 0x2f800000, v47
	v_mul_f32_e32 v50, 0x2f800000, v49
	v_mul_f32_e32 v21, 0x2f800000, v25
	v_fma_f32 v22, v45, s53, -v22
	v_cvt_pk_bf16_f32 v20, v44, v48
	v_cvt_pk_bf16_f32 v21, v50, v21
	v_cvt_pk_bf16_f32 v22, v1, v22
	v_lshlrev_b32_e32 v1, 16, v19
	v_fma_f32 v1, v23, s53, -v1
	v_and_b32_e32 v23, 0xffff0000, v19
	v_fma_f32 v23, v24, s53, -v23
	v_cvt_pk_bf16_f32 v23, v1, v23
	v_lshlrev_b32_e32 v1, 16, v20
	v_and_b32_e32 v24, 0xffff0000, v20
	v_fma_f32 v1, v43, s53, -v1
	v_fma_f32 v24, v47, s53, -v24
	v_cvt_pk_bf16_f32 v24, v1, v24
	v_lshlrev_b32_e32 v1, 16, v21
	v_mfma_f32_32x32x16_bf16 v[2:17], v[18:21], v[116:119], v[2:17]
	v_and_b32_e32 v18, 0xffff0000, v21
	v_fma_f32 v1, v49, s53, -v1
	v_fma_f32 v18, v25, s53, -v18
	v_cvt_pk_bf16_f32 v25, v1, v18
	s_waitcnt vmcnt(0)
; __device__ __forceinline__ unsigned cvtpk(float lo, float hi) { f32x2v_ v = {lo, hi}; bf16x2v_ b = __builtin_convertvector(v, bf16x2v_); return __builtin_bit_cast(unsigned, b); }
; __device__ __forceinline__ float bflo(unsigned w) { return __uint_as_float(w << 16); }
; __device__ __forceinline__ float bfhi(unsigned w) { return __uint_as_float(w & 0xffff0000u); }
; #define MFMA32(a, b, c) __builtin_amdgcn_mfma_f32_32x32x16_bf16((a), (b), (c), 0, 0, 0)
; template <int l> __device__ __forceinline__ void layer_body(const Args& args, LAS unsigned char* lds, const XcdBarrier& bar) {
;     ...
;                         const long long* ks = (const long long*)KSUM + ((size_t)(b * 4 + kvh) * 16 + (r & 15)) * 128 + 8 * hh;
; #pragma unroll
;                         for (int s = 0; s < 8; ++s) { f32x4 a0, a1;
; #pragma unroll
;                             for (int e = 0; e < 4; ++e) { a0[e] = (float)ks[16 * s + e] * (1.0f / 4294967296.0f); a1[e] = (float)ks[16 * s + 4 + e] * (1.0f / 4294967296.0f); }
;                             v4u hi; hi.x = cvtpk(a0[0], a0[1]); hi.y = cvtpk(a0[2], a0[3]); hi.z = cvtpk(a1[0], a1[1]); hi.w = cvtpk(a1[2], a1[3]);
;                             v4u lo; lo.x = cvtpk(a0[0] - bflo(hi.x), a0[1] - bfhi(hi.x)); lo.y = cvtpk(a0[2] - bflo(hi.y), a0[3] - bfhi(hi.y)); lo.z = cvtpk(a1[0] - bflo(hi.z), a1[1] - bfhi(hi.z)); lo.w = cvtpk(a1[2] - bflo(hi.w), a1[3] - bfhi(hi.w));
;                             gt = MFMA32(__builtin_bit_cast(bf16x8, hi), qf[s], gt); gt = MFMA32(__builtin_bit_cast(bf16x8, lo), qf[s], gt); }
	v_xor_b32_e32 v18, v34, v35
	v_ffbh_i32_e32 v1, v35
	v_ashrrev_i32_e32 v18, 31, v18
	v_add_u32_e32 v1, -1, v1
	v_add_u32_e32 v18, 32, v18
	v_min_u32_e32 v1, v1, v18
	v_lshlrev_b64 v[18:19], v1, v[34:35]
	v_min_u32_e32 v18, 1, v18
	v_or_b32_e32 v18, v19, v18
	v_cvt_f32_i32_e32 v20, v18
	v_xor_b32_e32 v19, v38, v39
	v_ffbh_i32_e32 v18, v39
	v_ashrrev_i32_e32 v19, 31, v19
	v_add_u32_e32 v18, -1, v18
	v_add_u32_e32 v19, 32, v19
	v_min_u32_e32 v21, v18, v19
	v_lshlrev_b64 v[18:19], v21, v[38:39]
	v_min_u32_e32 v18, 1, v18
	v_or_b32_e32 v18, v19, v18
	v_cvt_f32_i32_e32 v18, v18
	v_sub_u32_e32 v19, 32, v21
	v_sub_u32_e32 v1, 32, v1
	v_ldexp_f32 v1, v20, v1
	v_ldexp_f32 v43, v18, v19
	v_xor_b32_e32 v19, v36, v37
	v_ffbh_i32_e32 v18, v37
	v_ashrrev_i32_e32 v19, 31, v19
	v_add_u32_e32 v18, -1, v18
	v_add_u32_e32 v19, 32, v19
	v_min_u32_e32 v20, v18, v19
	v_lshlrev_b64 v[18:19], v20, v[36:37]
	v_min_u32_e32 v18, 1, v18
	v_or_b32_e32 v18, v19, v18
	v_xor_b32_e32 v19, v40, v41
	v_cvt_f32_i32_e32 v21, v18
	v_ffbh_i32_e32 v18, v41
	v_ashrrev_i32_e32 v19, 31, v19
	v_add_u32_e32 v18, -1, v18
	v_add_u32_e32 v19, 32, v19
	v_mfma_f32_32x32x16_bf16 v[2:17], v[22:25], v[116:119], v[2:17]
	v_min_u32_e32 v22, v18, v19
	v_lshlrev_b64 v[18:19], v22, v[40:41]
	v_min_u32_e32 v18, 1, v18
	v_or_b32_e32 v18, v19, v18
	v_cvt_f32_i32_e32 v18, v18
	v_sub_u32_e32 v19, 32, v22
	v_sub_u32_e32 v20, 32, v20
	global_load_dwordx4 v[22:25], v[170:171], off offset:400
	global_load_dwordx4 v[34:37], v[170:171], off offset:384
	v_ldexp_f32 v47, v18, v19
	v_xor_b32_e32 v19, v30, v31
	v_ffbh_i32_e32 v18, v31
	v_ashrrev_i32_e32 v19, 31, v19
	v_add_u32_e32 v18, -1, v18
	v_add_u32_e32 v19, 32, v19
	v_ldexp_f32 v45, v21, v20
	v_min_u32_e32 v20, v18, v19
	v_lshlrev_b64 v[18:19], v20, v[30:31]
	v_min_u32_e32 v18, 1, v18
	v_or_b32_e32 v18, v19, v18
	v_cvt_f32_i32_e32 v30, v18
	v_ffbh_i32_e32 v18, v27
	v_sub_u32_e32 v31, 32, v20
	v_add_u32_e32 v49, -1, v18
	global_load_dwordx4 v[18:21], v[170:171], off offset:432
	global_load_dwordx4 v[38:41], v[170:171], off offset:416
	v_xor_b32_e32 v50, v26, v27
	v_ashrrev_i32_e32 v50, 31, v50
	v_add_u32_e32 v50, 32, v50
	v_min_u32_e32 v49, v49, v50
	v_lshlrev_b64 v[26:27], v49, v[26:27]
	v_min_u32_e32 v26, 1, v26
	v_or_b32_e32 v26, v27, v26
	v_cvt_f32_i32_e32 v26, v26
	v_sub_u32_e32 v27, 32, v49
	v_mul_f32_e32 v42, 0x2f800000, v1
	v_mul_f32_e32 v46, 0x2f800000, v45
	v_ldexp_f32 v49, v26, v27
	v_xor_b32_e32 v27, v32, v33
	v_ffbh_i32_e32 v26, v33
	v_ashrrev_i32_e32 v27, 31, v27
	v_add_u32_e32 v26, -1, v26
	v_add_u32_e32 v27, 32, v27
	v_min_u32_e32 v51, v26, v27
	v_lshlrev_b64 v[26:27], v51, v[32:33]
	v_min_u32_e32 v26, 1, v26
	v_or_b32_e32 v26, v27, v26
	v_xor_b32_e32 v27, v28, v29
	v_cvt_f32_i32_e32 v32, v26
	v_ffbh_i32_e32 v26, v29
	v_ashrrev_i32_e32 v27, 31, v27
	v_add_u32_e32 v26, -1, v26
	v_add_u32_e32 v27, 32, v27
	v_sub_u32_e32 v33, 32, v51
	v_min_u32_e32 v51, v26, v27
	v_lshlrev_b64 v[26:27], v51, v[28:29]
	v_min_u32_e32 v26, 1, v26
	v_or_b32_e32 v26, v27, v26
	v_cvt_f32_i32_e32 v26, v26
	v_ldexp_f32 v31, v30, v31
	v_ldexp_f32 v32, v32, v33
	v_sub_u32_e32 v28, 32, v51
	v_mul_f32_e32 v30, 0x2f800000, v31
	v_mul_f32_e32 v27, 0x2f800000, v32
	v_ldexp_f32 v33, v26, v28
	v_cvt_pk_bf16_f32 v26, v42, v46
	v_cvt_pk_bf16_f32 v27, v30, v27
	v_lshlrev_b32_e32 v30, 16, v26
	v_fma_f32 v1, v1, s53, -v30
	v_and_b32_e32 v30, 0xffff0000, v26
	v_mul_f32_e32 v44, 0x2f800000, v43
	v_mul_f32_e32 v48, 0x2f800000, v47
	v_mul_f32_e32 v50, 0x2f800000, v49
	v_mul_f32_e32 v29, 0x2f800000, v33
	v_fma_f32 v30, v45, s53, -v30
	v_cvt_pk_bf16_f32 v28, v44, v48
	v_cvt_pk_bf16_f32 v29, v50, v29
	v_cvt_pk_bf16_f32 v30, v1, v30
	v_lshlrev_b32_e32 v1, 16, v27
	v_fma_f32 v1, v31, s53, -v1
	v_and_b32_e32 v31, 0xffff0000, v27
	v_fma_f32 v31, v32, s53, -v31
	v_cvt_pk_bf16_f32 v31, v1, v31
	v_lshlrev_b32_e32 v1, 16, v28
	v_and_b32_e32 v32, 0xffff0000, v28
	v_fma_f32 v1, v43, s53, -v1
	v_fma_f32 v32, v47, s53, -v32
	v_cvt_pk_bf16_f32 v32, v1, v32
	v_lshlrev_b32_e32 v1, 16, v29
	v_mfma_f32_32x32x16_bf16 v[2:17], v[26:29], v[120:123], v[2:17]
	v_and_b32_e32 v26, 0xffff0000, v29
	v_fma_f32 v1, v49, s53, -v1
	v_fma_f32 v26, v33, s53, -v26
	v_cvt_pk_bf16_f32 v33, v1, v26
	s_waitcnt vmcnt(0)
	v_xor_b32_e32 v26, v34, v35
	v_ffbh_i32_e32 v1, v35
	v_ashrrev_i32_e32 v26, 31, v26
	v_add_u32_e32 v1, -1, v1
	v_add_u32_e32 v26, 32, v26
	v_min_u32_e32 v1, v1, v26
	v_lshlrev_b64 v[26:27], v1, v[34:35]
	v_min_u32_e32 v26, 1, v26
	v_or_b32_e32 v26, v27, v26
	v_cvt_f32_i32_e32 v28, v26
	v_sub_u32_e32 v1, 32, v1
	v_xor_b32_e32 v27, v38, v39
	v_ffbh_i32_e32 v26, v39
	v_ashrrev_i32_e32 v27, 31, v27
	v_add_u32_e32 v26, -1, v26
	v_add_u32_e32 v27, 32, v27
	v_min_u32_e32 v29, v26, v27
	v_lshlrev_b64 v[26:27], v29, v[38:39]
	v_min_u32_e32 v26, 1, v26
	v_or_b32_e32 v26, v27, v26
	v_cvt_f32_i32_e32 v26, v26
	v_sub_u32_e32 v27, 32, v29
	v_ldexp_f32 v1, v28, v1
	v_mfma_f32_32x32x16_bf16 v[2:17], v[30:33], v[120:123], v[2:17]
	v_ldexp_f32 v43, v26, v27
	v_xor_b32_e32 v27, v36, v37
	v_ffbh_i32_e32 v26, v37
	v_ashrrev_i32_e32 v27, 31, v27
	v_add_u32_e32 v26, -1, v26
	v_add_u32_e32 v27, 32, v27
	v_min_u32_e32 v28, v26, v27
	v_lshlrev_b64 v[26:27], v28, v[36:37]
	v_min_u32_e32 v26, 1, v26
	v_or_b32_e32 v26, v27, v26
	v_xor_b32_e32 v27, v40, v41
	v_cvt_f32_i32_e32 v29, v26
	v_ffbh_i32_e32 v26, v41
	v_ashrrev_i32_e32 v27, 31, v27
	v_add_u32_e32 v26, -1, v26
	v_add_u32_e32 v27, 32, v27
	v_min_u32_e32 v30, v26, v27
	v_lshlrev_b64 v[26:27], v30, v[40:41]
	v_min_u32_e32 v26, 1, v26
	v_or_b32_e32 v26, v27, v26
	v_cvt_f32_i32_e32 v26, v26
	v_sub_u32_e32 v27, 32, v30
	global_load_dwordx4 v[30:33], v[170:171], off offset:528
; __device__ __forceinline__ unsigned cvtpk(float lo, float hi) { f32x2v_ v = {lo, hi}; bf16x2v_ b = __builtin_convertvector(v, bf16x2v_); return __builtin_bit_cast(unsigned, b); }
; __device__ __forceinline__ float bflo(unsigned w) { return __uint_as_float(w << 16); }
; __device__ __forceinline__ float bfhi(unsigned w) { return __uint_as_float(w & 0xffff0000u); }
; #define MFMA32(a, b, c) __builtin_amdgcn_mfma_f32_32x32x16_bf16((a), (b), (c), 0, 0, 0)
; template <int l> __device__ __forceinline__ void layer_body(const Args& args, LAS unsigned char* lds, const XcdBarrier& bar) {
;     ...
;                         const long long* ks = (const long long*)KSUM + ((size_t)(b * 4 + kvh) * 16 + (r & 15)) * 128 + 8 * hh;
; #pragma unroll
;                         for (int s = 0; s < 8; ++s) { f32x4 a0, a1;
; #pragma unroll
;                             for (int e = 0; e < 4; ++e) { a0[e] = (float)ks[16 * s + e] * (1.0f / 4294967296.0f); a1[e] = (float)ks[16 * s + 4 + e] * (1.0f / 4294967296.0f); }
;                             v4u hi; hi.x = cvtpk(a0[0], a0[1]); hi.y = cvtpk(a0[2], a0[3]); hi.z = cvtpk(a1[0], a1[1]); hi.w = cvtpk(a1[2], a1[3]);
;                             v4u lo; lo.x = cvtpk(a0[0] - bflo(hi.x), a0[1] - bfhi(hi.x)); lo.y = cvtpk(a0[2] - bflo(hi.y), a0[3] - bfhi(hi.y)); lo.z = cvtpk(a1[0] - bflo(hi.z), a1[1] - bfhi(hi.z)); lo.w = cvtpk(a1[2] - bflo(hi.w), a1[3] - bfhi(hi.w));
;                             gt = MFMA32(__builtin_bit_cast(bf16x8, hi), qf[s], gt); gt = MFMA32(__builtin_bit_cast(bf16x8, lo), qf[s], gt); }
	global_load_dwordx4 v[34:37], v[170:171], off offset:512
	v_sub_u32_e32 v28, 32, v28
	v_ldexp_f32 v47, v26, v27
	v_xor_b32_e32 v27, v22, v23
	v_ffbh_i32_e32 v26, v23
	v_ashrrev_i32_e32 v27, 31, v27
	v_add_u32_e32 v26, -1, v26
	v_add_u32_e32 v27, 32, v27
	v_min_u32_e32 v26, v26, v27
	v_lshlrev_b64 v[22:23], v26, v[22:23]
	v_min_u32_e32 v22, 1, v22
	v_or_b32_e32 v22, v23, v22
	v_sub_u32_e32 v23, 32, v26
	v_ffbh_i32_e32 v26, v19
	v_ldexp_f32 v45, v29, v28
	v_add_u32_e32 v49, -1, v26
	global_load_dwordx4 v[26:29], v[170:171], off offset:560
	global_load_dwordx4 v[38:41], v[170:171], off offset:544
	v_xor_b32_e32 v50, v18, v19
	v_ashrrev_i32_e32 v50, 31, v50
	v_add_u32_e32 v50, 32, v50
	v_min_u32_e32 v49, v49, v50
	v_lshlrev_b64 v[18:19], v49, v[18:19]
	v_min_u32_e32 v18, 1, v18
	v_or_b32_e32 v18, v19, v18
	v_cvt_f32_i32_e32 v18, v18
	v_sub_u32_e32 v19, 32, v49
	v_cvt_f32_i32_e32 v22, v22
	v_mul_f32_e32 v42, 0x2f800000, v1
	v_ldexp_f32 v49, v18, v19
	v_xor_b32_e32 v19, v24, v25
	v_ffbh_i32_e32 v18, v25
	v_ashrrev_i32_e32 v19, 31, v19
	v_add_u32_e32 v18, -1, v18
	v_add_u32_e32 v19, 32, v19
	v_min_u32_e32 v51, v18, v19
	v_lshlrev_b64 v[18:19], v51, v[24:25]
	v_min_u32_e32 v18, 1, v18
	v_or_b32_e32 v18, v19, v18
	v_xor_b32_e32 v19, v20, v21
	v_cvt_f32_i32_e32 v24, v18
	v_ffbh_i32_e32 v18, v21
	v_ashrrev_i32_e32 v19, 31, v19
	v_add_u32_e32 v18, -1, v18
	v_add_u32_e32 v19, 32, v19
	v_sub_u32_e32 v25, 32, v51
	v_min_u32_e32 v51, v18, v19
	v_lshlrev_b64 v[18:19], v51, v[20:21]
	v_min_u32_e32 v18, 1, v18
	v_or_b32_e32 v18, v19, v18
	v_cvt_f32_i32_e32 v18, v18
	v_mul_f32_e32 v46, 0x2f800000, v45
	v_ldexp_f32 v23, v22, v23
	v_ldexp_f32 v24, v24, v25
	v_sub_u32_e32 v20, 32, v51
	v_mul_f32_e32 v22, 0x2f800000, v23
	v_mul_f32_e32 v19, 0x2f800000, v24
	v_ldexp_f32 v25, v18, v20
	v_cvt_pk_bf16_f32 v18, v42, v46
	v_cvt_pk_bf16_f32 v19, v22, v19
	v_lshlrev_b32_e32 v22, 16, v18
	v_fma_f32 v1, v1, s53, -v22
	v_and_b32_e32 v22, 0xffff0000, v18
	v_mul_f32_e32 v44, 0x2f800000, v43
	v_mul_f32_e32 v48, 0x2f800000, v47
	v_mul_f32_e32 v50, 0x2f800000, v49
	v_mul_f32_e32 v21, 0x2f800000, v25
	v_fma_f32 v22, v45, s53, -v22
	v_cvt_pk_bf16_f32 v20, v44, v48
	v_cvt_pk_bf16_f32 v21, v50, v21
	v_cvt_pk_bf16_f32 v22, v1, v22
	v_lshlrev_b32_e32 v1, 16, v19
	v_fma_f32 v1, v23, s53, -v1
	v_and_b32_e32 v23, 0xffff0000, v19
	v_fma_f32 v23, v24, s53, -v23
	v_cvt_pk_bf16_f32 v23, v1, v23
	v_lshlrev_b32_e32 v1, 16, v20
	v_and_b32_e32 v24, 0xffff0000, v20
	v_fma_f32 v1, v43, s53, -v1
	v_fma_f32 v24, v47, s53, -v24
	v_cvt_pk_bf16_f32 v24, v1, v24
	v_lshlrev_b32_e32 v1, 16, v21
	v_mfma_f32_32x32x16_bf16 v[2:17], v[18:21], v[124:127], v[2:17]
	v_and_b32_e32 v18, 0xffff0000, v21
	v_fma_f32 v1, v49, s53, -v1
	v_fma_f32 v18, v25, s53, -v18
	v_cvt_pk_bf16_f32 v25, v1, v18
	s_waitcnt vmcnt(0)
	v_xor_b32_e32 v18, v34, v35
	v_ffbh_i32_e32 v1, v35
	v_ashrrev_i32_e32 v18, 31, v18
	v_add_u32_e32 v1, -1, v1
	v_add_u32_e32 v18, 32, v18
	v_min_u32_e32 v1, v1, v18
	v_lshlrev_b64 v[18:19], v1, v[34:35]
	v_min_u32_e32 v18, 1, v18
	v_or_b32_e32 v18, v19, v18
	v_cvt_f32_i32_e32 v20, v18
	v_xor_b32_e32 v19, v38, v39
	v_ffbh_i32_e32 v18, v39
	v_ashrrev_i32_e32 v19, 31, v19
	v_add_u32_e32 v18, -1, v18
	v_add_u32_e32 v19, 32, v19
	v_min_u32_e32 v21, v18, v19
	v_lshlrev_b64 v[18:19], v21, v[38:39]
	v_min_u32_e32 v18, 1, v18
	v_or_b32_e32 v18, v19, v18
	v_cvt_f32_i32_e32 v18, v18
	v_sub_u32_e32 v19, 32, v21
	v_sub_u32_e32 v1, 32, v1
	v_ldexp_f32 v1, v20, v1
	v_ldexp_f32 v43, v18, v19
	v_xor_b32_e32 v19, v36, v37
	v_ffbh_i32_e32 v18, v37
	v_ashrrev_i32_e32 v19, 31, v19
	v_add_u32_e32 v18, -1, v18
	v_add_u32_e32 v19, 32, v19
	v_min_u32_e32 v20, v18, v19
	v_lshlrev_b64 v[18:19], v20, v[36:37]
	v_min_u32_e32 v18, 1, v18
	v_or_b32_e32 v18, v19, v18
	v_xor_b32_e32 v19, v40, v41
	v_cvt_f32_i32_e32 v21, v18
	v_ffbh_i32_e32 v18, v41
	v_ashrrev_i32_e32 v19, 31, v19
	v_add_u32_e32 v18, -1, v18
	v_add_u32_e32 v19, 32, v19
	v_mfma_f32_32x32x16_bf16 v[2:17], v[22:25], v[124:127], v[2:17]
	v_min_u32_e32 v22, v18, v19
	v_lshlrev_b64 v[18:19], v22, v[40:41]
	v_min_u32_e32 v18, 1, v18
	v_or_b32_e32 v18, v19, v18
	v_cvt_f32_i32_e32 v18, v18
	v_sub_u32_e32 v19, 32, v22
	v_sub_u32_e32 v20, 32, v20
	global_load_dwordx4 v[22:25], v[170:171], off offset:656
	global_load_dwordx4 v[34:37], v[170:171], off offset:640
	v_ldexp_f32 v47, v18, v19
	v_xor_b32_e32 v19, v30, v31
	v_ffbh_i32_e32 v18, v31
	v_ashrrev_i32_e32 v19, 31, v19
	v_add_u32_e32 v18, -1, v18
	v_add_u32_e32 v19, 32, v19
	v_ldexp_f32 v45, v21, v20
	v_min_u32_e32 v20, v18, v19
	v_lshlrev_b64 v[18:19], v20, v[30:31]
	v_min_u32_e32 v18, 1, v18
	v_or_b32_e32 v18, v19, v18
	v_cvt_f32_i32_e32 v30, v18
	v_ffbh_i32_e32 v18, v27
	v_sub_u32_e32 v31, 32, v20
	v_add_u32_e32 v49, -1, v18
	global_load_dwordx4 v[18:21], v[170:171], off offset:688
	global_load_dwordx4 v[38:41], v[170:171], off offset:672
	v_xor_b32_e32 v50, v26, v27
	v_ashrrev_i32_e32 v50, 31, v50
	v_add_u32_e32 v50, 32, v50
	v_min_u32_e32 v49, v49, v50
	v_lshlrev_b64 v[26:27], v49, v[26:27]
	v_min_u32_e32 v26, 1, v26
	v_or_b32_e32 v26, v27, v26
	v_cvt_f32_i32_e32 v26, v26
	v_sub_u32_e32 v27, 32, v49
	v_mul_f32_e32 v42, 0x2f800000, v1
	v_mul_f32_e32 v46, 0x2f800000, v45
	v_ldexp_f32 v49, v26, v27
	v_xor_b32_e32 v27, v32, v33
	v_ffbh_i32_e32 v26, v33
	v_ashrrev_i32_e32 v27, 31, v27
	v_add_u32_e32 v26, -1, v26
	v_add_u32_e32 v27, 32, v27
	v_min_u32_e32 v51, v26, v27
	v_lshlrev_b64 v[26:27], v51, v[32:33]
	v_min_u32_e32 v26, 1, v26
	v_or_b32_e32 v26, v27, v26
	v_xor_b32_e32 v27, v28, v29
	v_cvt_f32_i32_e32 v32, v26
	v_ffbh_i32_e32 v26, v29
	v_ashrrev_i32_e32 v27, 31, v27
	v_add_u32_e32 v26, -1, v26
	v_add_u32_e32 v27, 32, v27
	v_sub_u32_e32 v33, 32, v51
	v_min_u32_e32 v51, v26, v27
	v_lshlrev_b64 v[26:27], v51, v[28:29]
	v_min_u32_e32 v26, 1, v26
	v_or_b32_e32 v26, v27, v26
	v_cvt_f32_i32_e32 v26, v26
	v_ldexp_f32 v31, v30, v31
	v_ldexp_f32 v32, v32, v33
	v_sub_u32_e32 v28, 32, v51
	v_mul_f32_e32 v30, 0x2f800000, v31
	v_mul_f32_e32 v27, 0x2f800000, v32
	v_ldexp_f32 v33, v26, v28
	v_cvt_pk_bf16_f32 v26, v42, v46
	v_cvt_pk_bf16_f32 v27, v30, v27
	v_lshlrev_b32_e32 v30, 16, v26
	v_fma_f32 v1, v1, s53, -v30
	v_and_b32_e32 v30, 0xffff0000, v26
	v_mul_f32_e32 v44, 0x2f800000, v43
	v_mul_f32_e32 v48, 0x2f800000, v47
	v_mul_f32_e32 v50, 0x2f800000, v49
	v_mul_f32_e32 v29, 0x2f800000, v33
	v_fma_f32 v30, v45, s53, -v30
	v_cvt_pk_bf16_f32 v28, v44, v48
	v_cvt_pk_bf16_f32 v29, v50, v29
	v_cvt_pk_bf16_f32 v30, v1, v30
	v_lshlrev_b32_e32 v1, 16, v27
	v_fma_f32 v1, v31, s53, -v1
	v_and_b32_e32 v31, 0xffff0000, v27
	v_fma_f32 v31, v32, s53, -v31
	v_cvt_pk_bf16_f32 v31, v1, v31
	v_lshlrev_b32_e32 v1, 16, v28
	v_and_b32_e32 v32, 0xffff0000, v28
	v_fma_f32 v1, v43, s53, -v1
	v_fma_f32 v32, v47, s53, -v32
	v_cvt_pk_bf16_f32 v32, v1, v32
	v_lshlrev_b32_e32 v1, 16, v29
	v_mfma_f32_32x32x16_bf16 v[2:17], v[26:29], v[128:131], v[2:17]
	v_and_b32_e32 v26, 0xffff0000, v29
	v_fma_f32 v1, v49, s53, -v1
	v_fma_f32 v26, v33, s53, -v26
	v_cvt_pk_bf16_f32 v33, v1, v26
	s_waitcnt vmcnt(0)
; __device__ __forceinline__ unsigned cvtpk(float lo, float hi) { f32x2v_ v = {lo, hi}; bf16x2v_ b = __builtin_convertvector(v, bf16x2v_); return __builtin_bit_cast(unsigned, b); }
; __device__ __forceinline__ float bflo(unsigned w) { return __uint_as_float(w << 16); }
; __device__ __forceinline__ float bfhi(unsigned w) { return __uint_as_float(w & 0xffff0000u); }
; #define MFMA32(a, b, c) __builtin_amdgcn_mfma_f32_32x32x16_bf16((a), (b), (c), 0, 0, 0)
; template <int l> __device__ __forceinline__ void layer_body(const Args& args, LAS unsigned char* lds, const XcdBarrier& bar) {
;     ...
;                         const long long* ks = (const long long*)KSUM + ((size_t)(b * 4 + kvh) * 16 + (r & 15)) * 128 + 8 * hh;
; #pragma unroll
;                         for (int s = 0; s < 8; ++s) { f32x4 a0, a1;
; #pragma unroll
;                             for (int e = 0; e < 4; ++e) { a0[e] = (float)ks[16 * s + e] * (1.0f / 4294967296.0f); a1[e] = (float)ks[16 * s + 4 + e] * (1.0f / 4294967296.0f); }
;                             v4u hi; hi.x = cvtpk(a0[0], a0[1]); hi.y = cvtpk(a0[2], a0[3]); hi.z = cvtpk(a1[0], a1[1]); hi.w = cvtpk(a1[2], a1[3]);
;                             v4u lo; lo.x = cvtpk(a0[0] - bflo(hi.x), a0[1] - bfhi(hi.x)); lo.y = cvtpk(a0[2] - bflo(hi.y), a0[3] - bfhi(hi.y)); lo.z = cvtpk(a1[0] - bflo(hi.z), a1[1] - bfhi(hi.z)); lo.w = cvtpk(a1[2] - bflo(hi.w), a1[3] - bfhi(hi.w));
;                             gt = MFMA32(__builtin_bit_cast(bf16x8, hi), qf[s], gt); gt = MFMA32(__builtin_bit_cast(bf16x8, lo), qf[s], gt); }
	v_xor_b32_e32 v26, v34, v35
	v_ffbh_i32_e32 v1, v35
	v_ashrrev_i32_e32 v26, 31, v26
	v_add_u32_e32 v1, -1, v1
	v_add_u32_e32 v26, 32, v26
	v_min_u32_e32 v1, v1, v26
	v_lshlrev_b64 v[26:27], v1, v[34:35]
	v_min_u32_e32 v26, 1, v26
	v_or_b32_e32 v26, v27, v26
	v_cvt_f32_i32_e32 v28, v26
	v_sub_u32_e32 v1, 32, v1
	v_xor_b32_e32 v27, v38, v39
	v_ffbh_i32_e32 v26, v39
	v_ashrrev_i32_e32 v27, 31, v27
	v_add_u32_e32 v26, -1, v26
	v_add_u32_e32 v27, 32, v27
	v_min_u32_e32 v29, v26, v27
	v_lshlrev_b64 v[26:27], v29, v[38:39]
	v_min_u32_e32 v26, 1, v26
	v_or_b32_e32 v26, v27, v26
	v_cvt_f32_i32_e32 v26, v26
	v_sub_u32_e32 v27, 32, v29
	v_ldexp_f32 v1, v28, v1
	v_mfma_f32_32x32x16_bf16 v[2:17], v[30:33], v[128:131], v[2:17]
	v_ldexp_f32 v43, v26, v27
	v_xor_b32_e32 v27, v36, v37
	v_ffbh_i32_e32 v26, v37
	v_ashrrev_i32_e32 v27, 31, v27
	v_add_u32_e32 v26, -1, v26
	v_add_u32_e32 v27, 32, v27
	v_min_u32_e32 v28, v26, v27
	v_lshlrev_b64 v[26:27], v28, v[36:37]
	v_min_u32_e32 v26, 1, v26
	v_or_b32_e32 v26, v27, v26
	v_xor_b32_e32 v27, v40, v41
	v_cvt_f32_i32_e32 v29, v26
	v_ffbh_i32_e32 v26, v41
	v_ashrrev_i32_e32 v27, 31, v27
	v_add_u32_e32 v26, -1, v26
	v_add_u32_e32 v27, 32, v27
	v_min_u32_e32 v30, v26, v27
	v_lshlrev_b64 v[26:27], v30, v[40:41]
	v_min_u32_e32 v26, 1, v26
	v_or_b32_e32 v26, v27, v26
	v_cvt_f32_i32_e32 v26, v26
	v_sub_u32_e32 v27, 32, v30
	global_load_dwordx4 v[30:33], v[170:171], off offset:784
	global_load_dwordx4 v[34:37], v[170:171], off offset:768
	v_sub_u32_e32 v28, 32, v28
	v_ldexp_f32 v47, v26, v27
	v_xor_b32_e32 v27, v22, v23
	v_ffbh_i32_e32 v26, v23
	v_ashrrev_i32_e32 v27, 31, v27
	v_add_u32_e32 v26, -1, v26
	v_add_u32_e32 v27, 32, v27
	v_min_u32_e32 v26, v26, v27
	v_lshlrev_b64 v[22:23], v26, v[22:23]
	v_min_u32_e32 v22, 1, v22
	v_or_b32_e32 v22, v23, v22
	v_sub_u32_e32 v23, 32, v26
	v_ffbh_i32_e32 v26, v19
	v_ldexp_f32 v45, v29, v28
	v_add_u32_e32 v49, -1, v26
	global_load_dwordx4 v[26:29], v[170:171], off offset:816
	global_load_dwordx4 v[38:41], v[170:171], off offset:800
	v_xor_b32_e32 v50, v18, v19
	v_ashrrev_i32_e32 v50, 31, v50
	v_add_u32_e32 v50, 32, v50
	v_min_u32_e32 v49, v49, v50
	v_lshlrev_b64 v[18:19], v49, v[18:19]
	v_min_u32_e32 v18, 1, v18
	v_or_b32_e32 v18, v19, v18
	v_cvt_f32_i32_e32 v18, v18
	v_sub_u32_e32 v19, 32, v49
	v_cvt_f32_i32_e32 v22, v22
	v_mul_f32_e32 v42, 0x2f800000, v1
	v_ldexp_f32 v49, v18, v19
	v_xor_b32_e32 v19, v24, v25
	v_ffbh_i32_e32 v18, v25
	v_ashrrev_i32_e32 v19, 31, v19
	v_add_u32_e32 v18, -1, v18
	v_add_u32_e32 v19, 32, v19
	v_min_u32_e32 v51, v18, v19
	v_lshlrev_b64 v[18:19], v51, v[24:25]
	v_min_u32_e32 v18, 1, v18
	v_or_b32_e32 v18, v19, v18
	v_xor_b32_e32 v19, v20, v21
	v_cvt_f32_i32_e32 v24, v18
	v_ffbh_i32_e32 v18, v21
	v_ashrrev_i32_e32 v19, 31, v19
	v_add_u32_e32 v18, -1, v18
	v_add_u32_e32 v19, 32, v19
	v_sub_u32_e32 v25, 32, v51
	v_min_u32_e32 v51, v18, v19
	v_lshlrev_b64 v[18:19], v51, v[20:21]
	v_min_u32_e32 v18, 1, v18
	v_or_b32_e32 v18, v19, v18
	v_cvt_f32_i32_e32 v18, v18
	v_mul_f32_e32 v46, 0x2f800000, v45
	v_ldexp_f32 v23, v22, v23
	v_ldexp_f32 v24, v24, v25
	v_sub_u32_e32 v20, 32, v51
	v_mul_f32_e32 v22, 0x2f800000, v23
	v_mul_f32_e32 v19, 0x2f800000, v24
	v_ldexp_f32 v25, v18, v20
	v_cvt_pk_bf16_f32 v18, v42, v46
	v_cvt_pk_bf16_f32 v19, v22, v19
	v_lshlrev_b32_e32 v22, 16, v18
	v_fma_f32 v1, v1, s53, -v22
	v_and_b32_e32 v22, 0xffff0000, v18
	v_mul_f32_e32 v44, 0x2f800000, v43
	v_mul_f32_e32 v48, 0x2f800000, v47
	v_mul_f32_e32 v50, 0x2f800000, v49
	v_mul_f32_e32 v21, 0x2f800000, v25
	v_fma_f32 v22, v45, s53, -v22
	v_cvt_pk_bf16_f32 v20, v44, v48
	v_cvt_pk_bf16_f32 v21, v50, v21
	v_cvt_pk_bf16_f32 v22, v1, v22
	v_lshlrev_b32_e32 v1, 16, v19
	v_fma_f32 v1, v23, s53, -v1
	v_and_b32_e32 v23, 0xffff0000, v19
	v_fma_f32 v23, v24, s53, -v23
	v_cvt_pk_bf16_f32 v23, v1, v23
	v_lshlrev_b32_e32 v1, 16, v20
	v_and_b32_e32 v24, 0xffff0000, v20
	v_fma_f32 v1, v43, s53, -v1
	v_fma_f32 v24, v47, s53, -v24
	v_cvt_pk_bf16_f32 v24, v1, v24
	v_lshlrev_b32_e32 v1, 16, v21
	v_mfma_f32_32x32x16_bf16 v[2:17], v[18:21], v[132:135], v[2:17]
	v_and_b32_e32 v18, 0xffff0000, v21
	v_fma_f32 v1, v49, s53, -v1
	v_fma_f32 v18, v25, s53, -v18
	v_cvt_pk_bf16_f32 v25, v1, v18
	s_waitcnt vmcnt(0)
	v_xor_b32_e32 v18, v34, v35
	v_ffbh_i32_e32 v1, v35
	v_ashrrev_i32_e32 v18, 31, v18
	v_add_u32_e32 v1, -1, v1
	v_add_u32_e32 v18, 32, v18
	v_min_u32_e32 v1, v1, v18
	v_lshlrev_b64 v[18:19], v1, v[34:35]
	v_min_u32_e32 v18, 1, v18
	v_or_b32_e32 v18, v19, v18
	v_cvt_f32_i32_e32 v20, v18
	v_xor_b32_e32 v19, v38, v39
	v_ffbh_i32_e32 v18, v39
	v_ashrrev_i32_e32 v19, 31, v19
	v_add_u32_e32 v18, -1, v18
	v_add_u32_e32 v19, 32, v19
	v_min_u32_e32 v21, v18, v19
	v_lshlrev_b64 v[18:19], v21, v[38:39]
	v_min_u32_e32 v18, 1, v18
	v_or_b32_e32 v18, v19, v18
	v_cvt_f32_i32_e32 v18, v18
	v_sub_u32_e32 v19, 32, v21
	v_sub_u32_e32 v1, 32, v1
	v_ldexp_f32 v1, v20, v1
	v_ldexp_f32 v43, v18, v19
	v_xor_b32_e32 v19, v36, v37
	v_ffbh_i32_e32 v18, v37
	v_ashrrev_i32_e32 v19, 31, v19
	v_add_u32_e32 v18, -1, v18
	v_add_u32_e32 v19, 32, v19
	v_min_u32_e32 v20, v18, v19
	v_lshlrev_b64 v[18:19], v20, v[36:37]
	v_min_u32_e32 v18, 1, v18
	v_or_b32_e32 v18, v19, v18
	v_xor_b32_e32 v19, v40, v41
	v_cvt_f32_i32_e32 v21, v18
	v_ffbh_i32_e32 v18, v41
	v_ashrrev_i32_e32 v19, 31, v19
	v_add_u32_e32 v18, -1, v18
	v_add_u32_e32 v19, 32, v19
	v_mfma_f32_32x32x16_bf16 v[2:17], v[22:25], v[132:135], v[2:17]
	v_min_u32_e32 v22, v18, v19
	v_lshlrev_b64 v[18:19], v22, v[40:41]
	v_min_u32_e32 v18, 1, v18
	v_or_b32_e32 v18, v19, v18
	v_cvt_f32_i32_e32 v18, v18
	v_sub_u32_e32 v19, 32, v22
	v_sub_u32_e32 v20, 32, v20
	v_ldexp_f32 v45, v21, v20
; __device__ __forceinline__ unsigned cvtpk(float lo, float hi) { f32x2v_ v = {lo, hi}; bf16x2v_ b = __builtin_convertvector(v, bf16x2v_); return __builtin_bit_cast(unsigned, b); }
; __device__ __forceinline__ float bflo(unsigned w) { return __uint_as_float(w << 16); }
; __device__ __forceinline__ float bfhi(unsigned w) { return __uint_as_float(w & 0xffff0000u); }
; #define MFMA32(a, b, c) __builtin_amdgcn_mfma_f32_32x32x16_bf16((a), (b), (c), 0, 0, 0)
; template <int l> __device__ __forceinline__ void layer_body(const Args& args, LAS unsigned char* lds, const XcdBarrier& bar) {
;     ...
;                         const long long* ks = (const long long*)KSUM + ((size_t)(b * 4 + kvh) * 16 + (r & 15)) * 128 + 8 * hh;
; #pragma unroll
;                         for (int s = 0; s < 8; ++s) { f32x4 a0, a1;
; #pragma unroll
;                             for (int e = 0; e < 4; ++e) { a0[e] = (float)ks[16 * s + e] * (1.0f / 4294967296.0f); a1[e] = (float)ks[16 * s + 4 + e] * (1.0f / 4294967296.0f); }
;                             v4u hi; hi.x = cvtpk(a0[0], a0[1]); hi.y = cvtpk(a0[2], a0[3]); hi.z = cvtpk(a1[0], a1[1]); hi.w = cvtpk(a1[2], a1[3]);
;                             v4u lo; lo.x = cvtpk(a0[0] - bflo(hi.x), a0[1] - bfhi(hi.x)); lo.y = cvtpk(a0[2] - bflo(hi.y), a0[3] - bfhi(hi.y)); lo.z = cvtpk(a1[0] - bflo(hi.z), a1[1] - bfhi(hi.z)); lo.w = cvtpk(a1[2] - bflo(hi.w), a1[3] - bfhi(hi.w));
;                             gt = MFMA32(__builtin_bit_cast(bf16x8, hi), qf[s], gt); gt = MFMA32(__builtin_bit_cast(bf16x8, lo), qf[s], gt); }
	v_ldexp_f32 v47, v18, v19
	v_ffbh_i32_e32 v18, v31
	v_add_u32_e32 v34, -1, v18
	v_xor_b32_e32 v18, v30, v31
	v_ashrrev_i32_e32 v18, 31, v18
	v_add_u32_e32 v35, 32, v18
	global_load_dwordx4 v[18:21], v[170:171], off offset:912
	global_load_dwordx4 v[22:25], v[170:171], off offset:896
	v_min_u32_e32 v34, v34, v35
	v_lshlrev_b64 v[30:31], v34, v[30:31]
	v_min_u32_e32 v30, 1, v30
	v_or_b32_e32 v30, v31, v30
	v_sub_u32_e32 v31, 32, v34
	v_ffbh_i32_e32 v34, v27
	v_add_u32_e32 v49, -1, v34
	global_load_dwordx4 v[34:37], v[170:171], off offset:944
	global_load_dwordx4 v[38:41], v[170:171], off offset:928
	v_xor_b32_e32 v50, v26, v27
	v_ashrrev_i32_e32 v50, 31, v50
	v_add_u32_e32 v50, 32, v50
	v_min_u32_e32 v49, v49, v50
	v_lshlrev_b64 v[26:27], v49, v[26:27]
	v_min_u32_e32 v26, 1, v26
	v_or_b32_e32 v26, v27, v26
	v_cvt_f32_i32_e32 v26, v26
	v_sub_u32_e32 v27, 32, v49
	v_cvt_f32_i32_e32 v30, v30
	v_mul_f32_e32 v42, 0x2f800000, v1
	v_ldexp_f32 v49, v26, v27
	v_xor_b32_e32 v27, v32, v33
	v_ffbh_i32_e32 v26, v33
	v_ashrrev_i32_e32 v27, 31, v27
	v_add_u32_e32 v26, -1, v26
	v_add_u32_e32 v27, 32, v27
	v_min_u32_e32 v51, v26, v27
	v_lshlrev_b64 v[26:27], v51, v[32:33]
	v_min_u32_e32 v26, 1, v26
	v_or_b32_e32 v26, v27, v26
	v_xor_b32_e32 v27, v28, v29
	v_cvt_f32_i32_e32 v32, v26
	v_ffbh_i32_e32 v26, v29
	v_ashrrev_i32_e32 v27, 31, v27
	v_add_u32_e32 v26, -1, v26
	v_add_u32_e32 v27, 32, v27
	v_sub_u32_e32 v33, 32, v51
	v_min_u32_e32 v51, v26, v27
	v_lshlrev_b64 v[26:27], v51, v[28:29]
	v_min_u32_e32 v26, 1, v26
	v_or_b32_e32 v26, v27, v26
	v_cvt_f32_i32_e32 v26, v26
	v_mul_f32_e32 v46, 0x2f800000, v45
	v_ldexp_f32 v31, v30, v31
	v_ldexp_f32 v32, v32, v33
	v_sub_u32_e32 v28, 32, v51
	v_mul_f32_e32 v30, 0x2f800000, v31
	v_mul_f32_e32 v27, 0x2f800000, v32
	v_ldexp_f32 v33, v26, v28
	v_cvt_pk_bf16_f32 v26, v42, v46
	v_cvt_pk_bf16_f32 v27, v30, v27
	v_lshlrev_b32_e32 v30, 16, v26
	v_fma_f32 v1, v1, s53, -v30
	v_and_b32_e32 v30, 0xffff0000, v26
	v_mul_f32_e32 v44, 0x2f800000, v43
	v_mul_f32_e32 v48, 0x2f800000, v47
	v_mul_f32_e32 v50, 0x2f800000, v49
	v_mul_f32_e32 v29, 0x2f800000, v33
	v_fma_f32 v30, v45, s53, -v30
	v_cvt_pk_bf16_f32 v28, v44, v48
	v_cvt_pk_bf16_f32 v29, v50, v29
	v_cvt_pk_bf16_f32 v30, v1, v30
	v_lshlrev_b32_e32 v1, 16, v27
	v_fma_f32 v1, v31, s53, -v1
	v_and_b32_e32 v31, 0xffff0000, v27
	v_fma_f32 v31, v32, s53, -v31
	v_cvt_pk_bf16_f32 v31, v1, v31
	v_lshlrev_b32_e32 v1, 16, v28
	v_and_b32_e32 v32, 0xffff0000, v28
	v_fma_f32 v1, v43, s53, -v1
	v_fma_f32 v32, v47, s53, -v32
	v_cvt_pk_bf16_f32 v32, v1, v32
	v_lshlrev_b32_e32 v1, 16, v29
	v_mfma_f32_32x32x16_bf16 v[2:17], v[26:29], v[136:139], v[2:17]
	v_and_b32_e32 v26, 0xffff0000, v29
	v_fma_f32 v1, v49, s53, -v1
	v_fma_f32 v26, v33, s53, -v26
	v_cvt_pk_bf16_f32 v33, v1, v26
	s_waitcnt vmcnt(0)
; __device__ __forceinline__ unsigned cvtpk(float lo, float hi) { f32x2v_ v = {lo, hi}; bf16x2v_ b = __builtin_convertvector(v, bf16x2v_); return __builtin_bit_cast(unsigned, b); }
; __device__ __forceinline__ float bflo(unsigned w) { return __uint_as_float(w << 16); }
; __device__ __forceinline__ float bfhi(unsigned w) { return __uint_as_float(w & 0xffff0000u); }
; #define MFMA32(a, b, c) __builtin_amdgcn_mfma_f32_32x32x16_bf16((a), (b), (c), 0, 0, 0)
; #define TOP3_INSERT(g, n) do { if ((g) > s0) { s2 = s1; i2 = i1; s1 = s0; i1 = i0; s0 = (g); i0 = (n); } else if ((g) > s1) { s2 = s1; i2 = i1; s1 = (g); i1 = (n); } else if ((g) > s2) { s2 = (g); i2 = (n); } } while (0)
; template <int l> __device__ __forceinline__ void layer_body(const Args& args, LAS unsigned char* lds, const XcdBarrier& bar) {
;     ...
;                         for (int s = 0; s < 8; ++s) { f32x4 a0, a1;
; #pragma unroll
;                             for (int e = 0; e < 4; ++e) { a0[e] = (float)ks[16 * s + e] * (1.0f / 4294967296.0f); a1[e] = (float)ks[16 * s + 4 + e] * (1.0f / 4294967296.0f); }
;                             v4u hi; hi.x = cvtpk(a0[0], a0[1]); hi.y = cvtpk(a0[2], a0[3]); hi.z = cvtpk(a1[0], a1[1]); hi.w = cvtpk(a1[2], a1[3]);
;                             v4u lo; lo.x = cvtpk(a0[0] - bflo(hi.x), a0[1] - bfhi(hi.x)); lo.y = cvtpk(a0[2] - bflo(hi.y), a0[3] - bfhi(hi.y)); lo.z = cvtpk(a1[0] - bflo(hi.z), a1[1] - bfhi(hi.z)); lo.w = cvtpk(a1[2] - bflo(hi.w), a1[3] - bfhi(hi.w));
;                             gt = MFMA32(__builtin_bit_cast(bf16x8, hi), qf[s], gt); gt = MFMA32(__builtin_bit_cast(bf16x8, lo), qf[s], gt); }
;                         float glo[8], ghi[8];
; #pragma unroll
;                         for (int i = 0; i < 8; ++i) { const float mine = gt[i], oth = __shfl_xor(mine, 32); glo[i] = hh ? oth : mine; ghi[i] = hh ? mine : oth; }
;                         float s0 = -INFINITY, s1 = -INFINITY, s2 = -INFINITY; int i0 = -1, i1 = -1, i2 = -1;
; #pragma unroll
;                         for (int n = 0; n < 16; ++n) { const float g = (n & 4) ? ghi[(n & 3) + 4 * (n >> 3)] : glo[(n & 3) + 4 * (n >> 3)]; if (n < own) TOP3_INSERT(g, n); }
;                         selmask = (i0 >= 0 ? 1u << i0 : 0u) | (i1 >= 0 ? 1u << i1 : 0u) | (i2 >= 0 ? 1u << i2 : 0u);
	v_xor_b32_e32 v26, v22, v23
	v_ffbh_i32_e32 v1, v23
	v_ashrrev_i32_e32 v26, 31, v26
	v_add_u32_e32 v1, -1, v1
	v_add_u32_e32 v26, 32, v26
	v_min_u32_e32 v1, v1, v26
	v_lshlrev_b64 v[22:23], v1, v[22:23]
	v_min_u32_e32 v22, 1, v22
	v_or_b32_e32 v22, v23, v22
	v_xor_b32_e32 v23, v38, v39
	v_cvt_f32_i32_e32 v26, v22
	v_ffbh_i32_e32 v22, v39
	v_ashrrev_i32_e32 v23, 31, v23
	v_add_u32_e32 v22, -1, v22
	v_add_u32_e32 v23, 32, v23
	v_min_u32_e32 v27, v22, v23
	v_lshlrev_b64 v[22:23], v27, v[38:39]
	v_min_u32_e32 v22, 1, v22
	v_or_b32_e32 v22, v23, v22
	v_cvt_f32_i32_e32 v22, v22
	v_sub_u32_e32 v23, 32, v27
	v_mfma_f32_32x32x16_bf16 v[2:17], v[30:33], v[136:139], v[2:17]
	v_xor_b32_e32 v30, v18, v19
	v_ldexp_f32 v27, v22, v23
	v_xor_b32_e32 v23, v24, v25
	v_ffbh_i32_e32 v22, v25
	v_ashrrev_i32_e32 v23, 31, v23
	v_add_u32_e32 v22, -1, v22
	v_add_u32_e32 v23, 32, v23
	v_min_u32_e32 v29, v22, v23
	v_lshlrev_b64 v[22:23], v29, v[24:25]
	v_min_u32_e32 v22, 1, v22
	v_or_b32_e32 v22, v23, v22
	v_xor_b32_e32 v23, v40, v41
	v_cvt_f32_i32_e32 v24, v22
	v_ffbh_i32_e32 v22, v41
	v_ashrrev_i32_e32 v23, 31, v23
	v_add_u32_e32 v22, -1, v22
	v_add_u32_e32 v23, 32, v23
	v_sub_u32_e32 v25, 32, v29
	v_min_u32_e32 v29, v22, v23
	v_lshlrev_b64 v[22:23], v29, v[40:41]
	v_min_u32_e32 v22, 1, v22
	v_or_b32_e32 v22, v23, v22
	v_ldexp_f32 v23, v24, v25
	v_sub_u32_e32 v25, 32, v29
	v_ffbh_i32_e32 v29, v19
	v_ashrrev_i32_e32 v30, 31, v30
	v_add_u32_e32 v29, -1, v29
	v_add_u32_e32 v30, 32, v30
	v_min_u32_e32 v29, v29, v30
	v_lshlrev_b64 v[18:19], v29, v[18:19]
	v_min_u32_e32 v18, 1, v18
	v_or_b32_e32 v18, v19, v18
	v_xor_b32_e32 v19, v34, v35
	v_cvt_f32_i32_e32 v30, v18
	v_ffbh_i32_e32 v18, v35
	v_ashrrev_i32_e32 v19, 31, v19
	v_add_u32_e32 v18, -1, v18
	v_add_u32_e32 v19, 32, v19
	v_min_u32_e32 v31, v18, v19
	v_lshlrev_b64 v[18:19], v31, v[34:35]
	v_min_u32_e32 v18, 1, v18
	v_or_b32_e32 v18, v19, v18
	v_cvt_f32_i32_e32 v18, v18
	v_sub_u32_e32 v19, 32, v31
	v_cvt_f32_i32_e32 v22, v22
	v_sub_u32_e32 v1, 32, v1
	v_ldexp_f32 v31, v18, v19
	v_xor_b32_e32 v19, v20, v21
	v_ffbh_i32_e32 v18, v21
	v_ashrrev_i32_e32 v19, 31, v19
	v_add_u32_e32 v18, -1, v18
	v_add_u32_e32 v19, 32, v19
	v_min_u32_e32 v33, v18, v19
	v_lshlrev_b64 v[18:19], v33, v[20:21]
	v_min_u32_e32 v18, 1, v18
	v_or_b32_e32 v18, v19, v18
	v_xor_b32_e32 v19, v36, v37
	v_cvt_f32_i32_e32 v20, v18
	v_ffbh_i32_e32 v18, v37
	v_ashrrev_i32_e32 v19, 31, v19
	v_add_u32_e32 v18, -1, v18
	v_add_u32_e32 v19, 32, v19
	v_sub_u32_e32 v21, 32, v33
	v_min_u32_e32 v33, v18, v19
	v_lshlrev_b64 v[18:19], v33, v[36:37]
	v_min_u32_e32 v18, 1, v18
	v_or_b32_e32 v18, v19, v18
	v_cvt_f32_i32_e32 v18, v18
	v_ldexp_f32 v1, v26, v1
	v_mul_f32_e32 v26, 0x2f800000, v1
	v_mul_f32_e32 v24, 0x2f800000, v23
	v_ldexp_f32 v25, v22, v25
	v_sub_u32_e32 v29, 32, v29
	v_ldexp_f32 v34, v20, v21
	v_sub_u32_e32 v20, 32, v33
	v_mul_f32_e32 v28, 0x2f800000, v27
	v_mul_f32_e32 v22, 0x2f800000, v25
	v_ldexp_f32 v29, v30, v29
	v_ldexp_f32 v33, v18, v20
	v_cvt_pk_bf16_f32 v18, v26, v24
	v_mul_f32_e32 v30, 0x2f800000, v29
	v_mul_f32_e32 v32, 0x2f800000, v31
	v_mul_f32_e32 v19, 0x2f800000, v34
	v_mul_f32_e32 v21, 0x2f800000, v33
	v_cvt_pk_bf16_f32 v20, v28, v22
	v_lshlrev_b32_e32 v22, 16, v18
	v_cvt_pk_bf16_f32 v19, v30, v19
	v_cvt_pk_bf16_f32 v21, v32, v21
	v_fma_f32 v1, v1, s53, -v22
	v_and_b32_e32 v22, 0xffff0000, v18
	v_fma_f32 v22, v23, s53, -v22
	v_cvt_pk_bf16_f32 v22, v1, v22
	v_lshlrev_b32_e32 v1, 16, v19
	v_and_b32_e32 v23, 0xffff0000, v19
	v_fma_f32 v1, v29, s53, -v1
	v_fma_f32 v23, v34, s53, -v23
	v_cvt_pk_bf16_f32 v23, v1, v23
	v_lshlrev_b32_e32 v1, 16, v20
	v_and_b32_e32 v24, 0xffff0000, v20
	v_fma_f32 v1, v27, s53, -v1
	v_fma_f32 v24, v25, s53, -v24
	v_mfma_f32_32x32x16_bf16 v[2:17], v[18:21], v[140:143], v[2:17]
	v_cvt_pk_bf16_f32 v24, v1, v24
	v_lshlrev_b32_e32 v1, 16, v21
	v_and_b32_e32 v18, 0xffff0000, v21
	v_fma_f32 v1, v31, s53, -v1
	v_fma_f32 v18, v33, s53, -v18
	v_cvt_pk_bf16_f32 v25, v1, v18
	v_xor_b32_e32 v1, 32, v182
	v_mov_b32_e32 v18, 0xff800000
	v_mfma_f32_32x32x16_bf16 v[2:17], v[22:25], v[140:143], v[2:17]
	s_nop 11
	v_and_b32_e32 v10, 64, v182
	v_add_u32_e32 v10, 64, v10
	v_cmp_lt_i32_e32 vcc, v1, v10
	v_mov_b32_e32 v17, -1
	s_nop 0
	v_cndmask_b32_e32 v1, v182, v1, vcc
	v_lshlrev_b32_e32 v1, 2, v1
	ds_bpermute_b32 v22, v1, v2
	ds_bpermute_b32 v21, v1, v3
	ds_bpermute_b32 v20, v1, v4
	ds_bpermute_b32 v19, v1, v5
	ds_bpermute_b32 v16, v1, v6
	ds_bpermute_b32 v15, v1, v7
	ds_bpermute_b32 v14, v1, v8
	ds_bpermute_b32 v10, v1, v9
	s_waitcnt lgkmcnt(0)
	v_cndmask_b32_e64 v11, v22, v2, s[4:5]
	v_cmp_nlg_f32_e32 vcc, v11, v18
	s_nop 1
	v_cndmask_b32_e64 v1, 0, -1, vcc
	v_cndmask_b32_e32 v12, v11, v18, vcc
	s_cbranch_scc1 .LBB0_1393
	v_cndmask_b32_e64 v23, v21, v3, s[4:5]
	v_cmp_ngt_f32_e32 vcc, v23, v12
	v_mov_b32_e32 v13, 1
	s_and_saveexec_b64 s[10:11], vcc
	s_cbranch_execz .LBB0_1391
	v_cmp_nlg_f32_e32 vcc, s54, v23
	v_mov_b32_e32 v11, 1
	s_and_saveexec_b64 s[48:49], vcc
	v_mov_b32_e32 v11, -1
	v_mov_b32_e32 v23, 0xff800000
	s_or_b64 exec, exec, s[48:49]
	v_mov_b32_e32 v13, v23
	v_swap_b32 v23, v12
	v_mov_b32_e32 v13, v1
	v_mov_b32_e32 v1, v11

; #define LAS __attribute__((address_space(3)))
; #define MFMA32(a, b, c) __builtin_amdgcn_mfma_f32_32x32x16_bf16((a), (b), (c), 0, 0, 0)
; #define DMA_PAIR(u_, pb_) do { DMA16(kgu + (size_t)(2 * (u_)) * 4096 + so, (pb_)); DMA16(kgu + (size_t)(2 * (u_) + 1) * 4096 + so, (pb_) + 8192); DMA16(vgu + (size_t)(2 * (u_)) * 4096 + so, 32768 + (pb_)); DMA16(vgu + (size_t)(2 * (u_) + 1) * 4096 + so, 32768 + (pb_) + 8192); } while (0)
; template <int l> __device__ __forceinline__ void layer_body(const Args& args, LAS unsigned char* lds, const XcdBarrier& bar) {
;     ...
;                     for (int u = 0; u <= umax; ++u) {
;                         if (u < umax) DMA_PAIR(u + 1, ((u + 1) & 1) * 16384);
;                         if (2 * u <= j) {
;                             const int ta = 2 * u; const bool hasb = (ta + 1 <= j);
;                             const LAS bf16* kl = (const LAS bf16*)(lds + (u & 1) * 16384) + (hh * 32 + pr) * 8; const LAS bf16* vl = (const LAS bf16*)(lds + 32768 + (u & 1) * 16384) + (hh * 128 + r) * 8;
;                             f32x16 st0, st1;
;                             { bf16x8 kfa[8], kfb[8];
; #pragma unroll
;                               for (int s = 0; s < 8; ++s) { kfa[s] = *(const LAS bf16x8*)(kl + s * 512); kfb[s] = *(const LAS bf16x8*)(kl + 4096 + s * 512); }
; #pragma unroll
;                               for (int i = 0; i < 16; ++i) { st0[i] = 0.f; st1[i] = 0.f; }
; #pragma unroll
;                               for (int s = 0; s < 8; ++s) { st0 = MFMA32(kfa[s], qf[s], st0); st1 = MFMA32(kfb[s], qf[s], st1); } }
.LBB0_1509:
	s_add_i32 s75, s75, 1
	s_add_u32 s48, s48, 0x4000
	s_addc_u32 s49, s49, 0
	s_add_i32 s74, s74, 64
	s_add_i32 s63, s63, 2
	s_sub_i32 s67, s67, 64
	v_add_u32_e32 v192, 0xffffff00, v192
	s_bitcmp1_b32 s48, 14
	s_cbranch_scc1 .LBB0_1510
	s_waitcnt vmcnt(0) lgkmcnt(0)
	s_barrier
	s_cmp_eq_u32 s64, s75
	s_cbranch_scc1 .LBB0_1379
.LBB0_1510:
	s_cmp_gt_i32 s63, s61
	s_cbranch_scc1 .Lmoba_skipdma
	s_cmp_ge_i32 s75, s65
	s_cbranch_scc1 .Lmoba_qk_nodma
	s_and_b32 s76, s48, 0x4000
	s_and_b32 s50, s48, 0x8000
	s_lshl_b32 s50, s50, 1
	s_or_b32 s76, s76, s50
	v_add_u32_e32 v1, s76, v145
	ds_read_b128 v[218:221], v1
	ds_read_b128 v[222:225], v1 offset:8192
	ds_read_b128 v[226:229], v1 offset:1024
	ds_read_b128 v[230:233], v1 offset:9216
	ds_read_b128 v[234:237], v1 offset:2048
	ds_read_b128 v[238:241], v1 offset:10240
	ds_read_b128 v[242:245], v1 offset:3072
	ds_read_b128 v[246:249], v1 offset:11264
	s_lshr_b32 s77, s75, 2
	v_add_u32_e32 v202, s76, v179
	s_and_b32 s10, s48, 0x4000
	s_xor_b32 s50, s48, 0x8000
	s_and_b32 s50, s50, 0x8000
	s_lshl_b32 s50, s50, 1
	s_or_b32 s10, s10, s50
	s_add_i32 s10, s33, s10
	s_add_u32 s100, s48, 0x4000
	s_addc_u32 s101, s49, 0
	v_lshl_add_u64 v[2:3], v[156:157], 0, s[100:101]
	v_lshl_add_u64 v[4:5], v[2:3], 0, s[36:37]
	v_lshl_add_u64 v[6:7], v[2:3], 0, s[38:39]
	v_lshl_add_u64 v[8:9], v[2:3], 0, s[42:43]
	v_lshl_add_u64 v[10:11], v[2:3], 0, s[44:45]
	s_waitcnt lgkmcnt(7)
	v_mfma_f32_32x32x16_bf16 v[80:95], v[218:221], v[112:115], 0
	ds_read_b128 v[218:221], v1 offset:4096
	s_waitcnt lgkmcnt(7)
	v_mfma_f32_32x32x16_bf16 v[96:111], v[222:225], v[112:115], 0
	ds_read_b128 v[222:225], v1 offset:12288
	s_mov_b32 m0, s10
	s_waitcnt lgkmcnt(7)
	v_mfma_f32_32x32x16_bf16 v[80:95], v[226:229], v[116:119], v[80:95]
	ds_read_b128 v[226:229], v1 offset:5120
	global_load_lds_dwordx4 v[4:5], off
	s_waitcnt lgkmcnt(7)
	v_mfma_f32_32x32x16_bf16 v[96:111], v[230:233], v[116:119], v[96:111]
	ds_read_b128 v[230:233], v1 offset:13312
	s_waitcnt lgkmcnt(7)
	v_mfma_f32_32x32x16_bf16 v[80:95], v[234:237], v[120:123], v[80:95]
	ds_read_b128 v[234:237], v1 offset:6144
	s_add_i32 m0, s10, 0x2000
	s_waitcnt lgkmcnt(7)
	v_mfma_f32_32x32x16_bf16 v[96:111], v[238:241], v[120:123], v[96:111]
	ds_read_b128 v[238:241], v1 offset:14336
	global_load_lds_dwordx4 v[6:7], off
	s_waitcnt lgkmcnt(7)
	v_mfma_f32_32x32x16_bf16 v[80:95], v[242:245], v[124:127], v[80:95]
	ds_read_b128 v[242:245], v1 offset:7168
	s_waitcnt lgkmcnt(7)
	v_mfma_f32_32x32x16_bf16 v[96:111], v[246:249], v[124:127], v[96:111]
	ds_read_b128 v[246:249], v1 offset:15360
	s_add_i32 m0, s10, 0x8000
	s_waitcnt lgkmcnt(7)
	v_mfma_f32_32x32x16_bf16 v[80:95], v[218:221], v[128:131], v[80:95]
	global_load_lds_dwordx4 v[8:9], off
	s_waitcnt lgkmcnt(6)
	v_mfma_f32_32x32x16_bf16 v[96:111], v[222:225], v[128:131], v[96:111]
	s_waitcnt lgkmcnt(5)
	v_mfma_f32_32x32x16_bf16 v[80:95], v[226:229], v[132:135], v[80:95]
	s_add_i32 m0, s10, 0xa000
	s_waitcnt lgkmcnt(4)
	v_mfma_f32_32x32x16_bf16 v[96:111], v[230:233], v[132:135], v[96:111]
	global_load_lds_dwordx4 v[10:11], off
	s_waitcnt lgkmcnt(3)
	v_mfma_f32_32x32x16_bf16 v[80:95], v[234:237], v[136:139], v[80:95]
	s_waitcnt lgkmcnt(2)
	v_mfma_f32_32x32x16_bf16 v[96:111], v[238:241], v[136:139], v[96:111]
	s_waitcnt lgkmcnt(1)
	v_mfma_f32_32x32x16_bf16 v[80:95], v[242:245], v[140:143], v[80:95]
	s_waitcnt lgkmcnt(0)
	v_mfma_f32_32x32x16_bf16 v[96:111], v[246:249], v[140:143], v[96:111]
	s_branch .Lmoba_qk_done
.Lmoba_skipdma:
	s_cmp_ge_i32 s75, s65
	s_cbranch_scc1 .LBB0_1509
	s_and_b32 s10, s48, 0x4000
	s_xor_b32 s50, s48, 0x8000
	s_and_b32 s50, s50, 0x8000
	s_lshl_b32 s50, s50, 1
	s_or_b32 s10, s10, s50
	s_add_i32 s10, s33, s10
	s_add_u32 s100, s48, 0x4000
	s_addc_u32 s101, s49, 0
	v_lshl_add_u64 v[2:3], v[156:157], 0, s[100:101]
	v_lshl_add_u64 v[4:5], v[2:3], 0, s[36:37]
	s_mov_b32 m0, s10
	s_nop 0
	global_load_lds_dwordx4 v[4:5], off
	v_lshl_add_u64 v[4:5], v[2:3], 0, s[38:39]
	s_add_i32 m0, s10, 0x2000
	s_nop 0
	global_load_lds_dwordx4 v[4:5], off
	v_lshl_add_u64 v[4:5], v[2:3], 0, s[42:43]
	s_add_i32 m0, s10, 0x8000
	v_lshl_add_u64 v[2:3], v[2:3], 0, s[44:45]
	global_load_lds_dwordx4 v[4:5], off
	s_add_i32 m0, s10, 0xa000
	s_nop 0
	global_load_lds_dwordx4 v[2:3], off
	s_branch .LBB0_1509
.Lmoba_qk_nodma:
	s_and_b32 s76, s48, 0x4000
	s_and_b32 s50, s48, 0x8000
	s_lshl_b32 s50, s50, 1
	s_or_b32 s76, s76, s50
	v_add_u32_e32 v1, s76, v145
	ds_read_b128 v[218:221], v1
	ds_read_b128 v[222:225], v1 offset:8192
	ds_read_b128 v[226:229], v1 offset:1024
	ds_read_b128 v[230:233], v1 offset:9216
	ds_read_b128 v[234:237], v1 offset:2048
	ds_read_b128 v[238:241], v1 offset:10240
	ds_read_b128 v[242:245], v1 offset:3072
	ds_read_b128 v[246:249], v1 offset:11264
	s_lshr_b32 s77, s75, 2
	s_cmp_lt_i32 s63, s61
	s_mov_b64 s[10:11], -1
	v_add_u32_e32 v202, s76, v179
	s_waitcnt lgkmcnt(7)
	v_mfma_f32_32x32x16_bf16 v[80:95], v[218:221], v[112:115], 0
	ds_read_b128 v[218:221], v1 offset:4096
	s_waitcnt lgkmcnt(7)
	v_mfma_f32_32x32x16_bf16 v[96:111], v[222:225], v[112:115], 0
	ds_read_b128 v[222:225], v1 offset:12288
	s_waitcnt lgkmcnt(7)
	v_mfma_f32_32x32x16_bf16 v[80:95], v[226:229], v[116:119], v[80:95]
	ds_read_b128 v[226:229], v1 offset:5120
	s_waitcnt lgkmcnt(7)
	v_mfma_f32_32x32x16_bf16 v[96:111], v[230:233], v[116:119], v[96:111]
	ds_read_b128 v[230:233], v1 offset:13312
	s_waitcnt lgkmcnt(7)
	v_mfma_f32_32x32x16_bf16 v[80:95], v[234:237], v[120:123], v[80:95]
	ds_read_b128 v[234:237], v1 offset:6144
	s_waitcnt lgkmcnt(7)
	v_mfma_f32_32x32x16_bf16 v[96:111], v[238:241], v[120:123], v[96:111]
	ds_read_b128 v[238:241], v1 offset:14336
	s_waitcnt lgkmcnt(7)
	v_mfma_f32_32x32x16_bf16 v[80:95], v[242:245], v[124:127], v[80:95]
	ds_read_b128 v[242:245], v1 offset:7168
	s_waitcnt lgkmcnt(7)
	v_mfma_f32_32x32x16_bf16 v[96:111], v[246:249], v[124:127], v[96:111]
	ds_read_b128 v[246:249], v1 offset:15360
	s_waitcnt lgkmcnt(7)
	v_mfma_f32_32x32x16_bf16 v[80:95], v[218:221], v[128:131], v[80:95]
	s_waitcnt lgkmcnt(6)
	v_mfma_f32_32x32x16_bf16 v[96:111], v[222:225], v[128:131], v[96:111]
	s_waitcnt lgkmcnt(5)
	v_mfma_f32_32x32x16_bf16 v[80:95], v[226:229], v[132:135], v[80:95]
	s_waitcnt lgkmcnt(4)
	v_mfma_f32_32x32x16_bf16 v[96:111], v[230:233], v[132:135], v[96:111]
	s_waitcnt lgkmcnt(3)
	v_mfma_f32_32x32x16_bf16 v[80:95], v[234:237], v[136:139], v[80:95]
	s_waitcnt lgkmcnt(2)
	v_mfma_f32_32x32x16_bf16 v[96:111], v[238:241], v[136:139], v[96:111]
	s_waitcnt lgkmcnt(1)
	v_mfma_f32_32x32x16_bf16 v[80:95], v[242:245], v[140:143], v[80:95]
	s_waitcnt lgkmcnt(0)
	v_mfma_f32_32x32x16_bf16 v[96:111], v[246:249], v[140:143], v[96:111]
